# hyena: spectrum slice L2 prefetch at item start; boundary cache cx written straight from the output loop (64/32 serialized global round trips per item removed); prep: 8 weight loads in flight per tran
# speedup vs baseline: 1.1502x; 1.0174x over previous
; __device__ __forceinline__ int otid() { int t = threadIdx.x; asm volatile("" : "+v"(t)); return t; }
; #define LAS __attribute__((address_space(3)))
; template <int L, int N, int NB> DEVQ void hyena_item(const Params& P, LAS unsigned char* lds, bf16* pT, float* zs, int d, size_t m0, const cf* specd, const float* cornerd) {
;     constexpr int NG = L / 8;
;     static_assert(L % 8 == 0 && (N / 16) % NTHR == 0, "groups; thread e/8 owns positions e and N/2 + e");
;     const int tid0_ = otid(); const int tid = tid0_;
;     LAS cf* X = (LAS cf*)lds;
;     LAS float* cx = (LAS float*)(lds + MISC_OFF);
;     LAS float* cfs = cx + 64 * NB;
;     const float* cw = P.in[7]; const float* cb = P.in[8];
;     { const float w0 = cw[d], w1 = cw[3072 + d], w2 = cw[6144 + d], bs = cb[d];
; #pragma unroll
;       for (int nb = 0; nb < NB; ++nb) {
;         const bf16* pv = pT + (size_t)d * TPAD + m0 + (size_t)nb * 2 * L; float* zb = zs + nb * 2 * L; LAS cf* Xb = X + nb; LAS float* cxb = cx + 64 * nb;
.LBB0_234:
	s_or_b64 exec, exec, s[0:1]
	s_lshl_b64 s[0:1], s[22:23], 16
	v_readlane_b32 s4, v255, 44
	s_add_u32 s72, s4, s0
	v_readlane_b32 s0, v255, 46
	s_addc_u32 s73, s0, s1
	v_lshlrev_b32_e32 v233, 7, v60
	global_load_dword v232, v233, s[72:73]
	s_add_u32 s23, s68, s28
	s_addc_u32 s59, s69, 0
	s_add_u32 s30, s23, s3
	s_addc_u32 s31, s59, s2
	s_add_u32 s34, s30, 0x2020
	s_addc_u32 s35, s31, 0
	s_add_u32 s36, s30, 0x4040
	s_addc_u32 s37, s31, 0
	s_add_u32 s76, s30, 0x6060
	s_addc_u32 s77, s31, 0
	s_mov_b32 s90, 0
	s_mov_b64 s[80:81], 0
	s_mov_b64 s[78:79], -1
	s_waitcnt lgkmcnt(0)
	s_barrier
	s_branch .LBB0_237

; #define LAS __attribute__((address_space(3)))
; template <int L, int N, int NB> DEVQ void hyena_item(const Params& P, LAS unsigned char* lds, bf16* pT, float* zs, int d, size_t m0, const cf* specd, const float* cornerd) {
;     ...
;                 if (o == 0) {
;                     *(f32x4*)(zb + t0) = (f32x4){ya[0], ya[1], ya[2], ya[3]}; *(f32x4*)(zb + t0 + 4) = (f32x4){ya[4], ya[5], ya[6], ya[7]};
;                     *(f32x4*)(zb + L + t0) = (f32x4){yb[0], yb[1], yb[2], yb[3]}; *(f32x4*)(zb + L + t0 + 4) = (f32x4){yb[4], yb[5], yb[6], yb[7]};
; #pragma unroll
;                     for (int e = 0; e < 8; ++e) Xb[NB * swz(t0 + e)] = cf{ya[e], yb[e]};
;     ...
;                 for (int nb = 0; nb < NB; ++nb) { const float* zb = zs + nb * 2 * L; LAS float* cxb = cx + 64 * nb;
; #pragma unroll
;                     for (int e = 0; e < 8; ++e) { const int t = tid * 8 + e; cxb[t] = zb[t]; cxb[32 + t] = zb[L + t]; cxb[16 + t] = zb[N / 2 + t]; cxb[48 + t] = zb[L + N / 2 + t]; } } }
.LBB0_353:
	s_andn2_b64 vcc, exec, s[0:1]
	s_cbranch_vccnz .LBB0_276
	flat_store_dwordx4 v[58:59], v[8:11]
	flat_store_dwordx4 v[58:59], v[4:7] offset:16
	flat_store_dwordx4 v[56:57], v[0:3]
	flat_store_dwordx4 v[56:57], v[12:15] offset:16
	v_cmp_gt_i32_e64 s[94:95], 2, v141
	v_lshrrev_b32_e32 v16, 9, v141
	v_and_b32_e32 v17, 1, v141
	v_cmp_ne_u32_e64 s[96:97], 0, v16
	v_lshlrev_b32_e32 v17, 5, v17
	s_mov_b32 s28, 0x20000
	s_or_b64 s[94:95], s[94:95], s[96:97]
	v_cndmask_b32_e64 v16, 0, 64, s[96:97]
	v_add3_u32 v16, v17, v16, s28
	s_and_saveexec_b64 s[96:97], s[94:95]
	ds_write_b128 v16, v[8:11]
	ds_write_b128 v16, v[4:7] offset:16
	ds_write_b128 v16, v[0:3] offset:128
	ds_write_b128 v16, v[12:15] offset:144
	s_or_b64 exec, exec, s[96:97]
	v_mov_b32_e32 v17, v0
	v_mov_b32_e32 v0, v9
	ds_write_b64 v143, v[0:1]
	v_mov_b32_e32 v0, v10
	v_mov_b32_e32 v1, v2
	ds_write_b64 v144, v[0:1]
	v_mov_b32_e32 v0, v4
	v_mov_b32_e32 v1, v12
	v_mov_b32_e32 v16, v8
	v_mov_b32_e32 v2, v11
	ds_write_b64 v146, v[0:1]
	v_mov_b32_e32 v12, v5
	v_mov_b32_e32 v0, v6
	v_mov_b32_e32 v1, v14
	v_mov_b32_e32 v14, v7
	ds_write_b64 v142, v[16:17]
	ds_write_b64 v145, v[2:3]
	ds_write_b64 v147, v[12:13]
	ds_write_b64 v148, v[0:1]
	ds_write_b64 v149, v[14:15]
	s_branch .LBB0_276

; #define LAS __attribute__((address_space(3)))
; template <int L, int N, int NB> DEVQ void hyena_item(const Params& P, LAS unsigned char* lds, bf16* pT, float* zs, int d, size_t m0, const cf* specd, const float* cornerd) {
;     ...
;                 if (o == 0) {
;                     *(f32x4*)(zb + t0) = (f32x4){ya[0], ya[1], ya[2], ya[3]}; *(f32x4*)(zb + t0 + 4) = (f32x4){ya[4], ya[5], ya[6], ya[7]};
;                     *(f32x4*)(zb + L + t0) = (f32x4){yb[0], yb[1], yb[2], yb[3]}; *(f32x4*)(zb + L + t0 + 4) = (f32x4){yb[4], yb[5], yb[6], yb[7]};
; #pragma unroll
;                     for (int e = 0; e < 8; ++e) Xb[NB * swz(t0 + e)] = cf{ya[e], yb[e]};
;     ...
;                 for (int nb = 0; nb < NB; ++nb) { const float* zb = zs + nb * 2 * L; LAS float* cxb = cx + 64 * nb;
; #pragma unroll
;                     for (int e = 0; e < 8; ++e) { const int t = tid * 8 + e; cxb[t] = zb[t]; cxb[32 + t] = zb[L + t]; cxb[16 + t] = zb[N / 2 + t]; cxb[48 + t] = zb[L + N / 2 + t]; } } }
.LBB0_437:
	s_andn2_b64 vcc, exec, s[0:1]
	s_cbranch_vccnz .LBB0_360
	flat_store_dwordx4 v[58:59], v[8:11]
	flat_store_dwordx4 v[58:59], v[4:7] offset:16
	flat_store_dwordx4 v[56:57], v[0:3]
	flat_store_dwordx4 v[56:57], v[12:15] offset:16
	v_cmp_gt_i32_e64 s[92:93], 2, v118
	v_lshrrev_b32_e32 v16, 9, v118
	v_and_b32_e32 v17, 1, v118
	v_cmp_ne_u32_e64 s[94:95], 0, v16
	v_lshlrev_b32_e32 v17, 5, v17
	s_mov_b32 s28, 0x20100
	s_or_b64 s[92:93], s[92:93], s[94:95]
	v_cndmask_b32_e64 v16, 0, 64, s[94:95]
	v_add3_u32 v16, v17, v16, s28
	s_and_saveexec_b64 s[94:95], s[92:93]
	ds_write_b128 v16, v[8:11]
	ds_write_b128 v16, v[4:7] offset:16
	ds_write_b128 v16, v[0:3] offset:128
	ds_write_b128 v16, v[12:15] offset:144
	s_or_b64 exec, exec, s[94:95]
	v_mov_b32_e32 v17, v0
	v_mov_b32_e32 v0, v9
	ds_write_b64 v120, v[0:1] offset:8
	v_mov_b32_e32 v0, v10
	v_mov_b32_e32 v1, v2
	ds_write_b64 v121, v[0:1] offset:8
	v_mov_b32_e32 v0, v4
	v_mov_b32_e32 v1, v12
	v_mov_b32_e32 v16, v8
	v_mov_b32_e32 v2, v11
	ds_write_b64 v123, v[0:1] offset:8
	v_mov_b32_e32 v12, v5
	v_mov_b32_e32 v0, v6
	v_mov_b32_e32 v1, v14
	v_mov_b32_e32 v14, v7
	ds_write_b64 v119, v[16:17] offset:8
	ds_write_b64 v122, v[2:3] offset:8
	ds_write_b64 v124, v[12:13] offset:8
	ds_write_b64 v125, v[0:1] offset:8
	ds_write_b64 v126, v[14:15] offset:8
	s_branch .LBB0_360

; #define LAS __attribute__((address_space(3)))
; template <int L, int N, int NB> DEVQ void hyena_item(const Params& P, LAS unsigned char* lds, bf16* pT, float* zs, int d, size_t m0, const cf* specd, const float* cornerd) {
;     ...
;         if (o == 0) {
;             __syncthreads();
;             if (tid < 2) {
; #pragma unroll
;                 for (int nb = 0; nb < NB; ++nb) { const float* zb = zs + nb * 2 * L; LAS float* cxb = cx + 64 * nb;
; #pragma unroll
;                     for (int e = 0; e < 8; ++e) { const int t = tid * 8 + e; cxb[t] = zb[t]; cxb[32 + t] = zb[L + t]; cxb[16 + t] = zb[N / 2 + t]; cxb[48 + t] = zb[L + N / 2 + t]; } } }
;             __syncthreads();
.LBB0_442:
	s_or_b64 exec, exec, s[0:1]
	s_mov_b64 s[80:81], -1
	s_andn2_b64 vcc, exec, s[78:79]
	s_mov_b64 s[0:1], -1
	s_waitcnt lgkmcnt(0)
	s_cbranch_vccnz .LBB0_236
	v_cmp_gt_i32_e32 vcc, 2, v61
	s_barrier
	s_and_saveexec_b64 s[0:1], vcc
	s_cbranch_execz .LBB0_235
	s_branch .LBB0_235

; __device__ __forceinline__ int otid() { int t = threadIdx.x; asm volatile("" : "+v"(t)); return t; }
; #define LAS __attribute__((address_space(3)))
; template <int L, int N, int NB> DEVQ void hyena_item(const Params& P, LAS unsigned char* lds, bf16* pT, float* zs, int d, size_t m0, const cf* specd, const float* cornerd) {
;     constexpr int NG = L / 8;
;     static_assert(L % 8 == 0 && (N / 16) % NTHR == 0, "groups; thread e/8 owns positions e and N/2 + e");
;     const int tid0_ = otid(); const int tid = tid0_;
;     LAS cf* X = (LAS cf*)lds;
;     LAS float* cx = (LAS float*)(lds + MISC_OFF);
;     LAS float* cfs = cx + 64 * NB;
;     const float* cw = P.in[7]; const float* cb = P.in[8];
;     { const float w0 = cw[d], w1 = cw[3072 + d], w2 = cw[6144 + d], bs = cb[d];
; #pragma unroll
;       for (int nb = 0; nb < NB; ++nb) {
;         const bf16* pv = pT + (size_t)d * TPAD + m0 + (size_t)nb * 2 * L; float* zb = zs + nb * 2 * L; LAS cf* Xb = X + nb; LAS float* cxb = cx + 64 * nb;
.LBB0_470:
	s_or_b64 exec, exec, s[0:1]
	s_lshl_b64 s[0:1], s[12:13], 17
	v_readlane_b32 s2, v255, 15
	s_add_u32 s22, s2, s0
	v_readlane_b32 s0, v255, 14
	s_addc_u32 s23, s0, s1
	v_lshlrev_b32_e32 v233, 7, v40
	v_add_u32_e32 v235, 0x10000, v233
	global_load_dword v232, v233, s[22:23]
	global_load_dword v234, v235, s[22:23]
	s_add_i32 s13, s12, 0x400
	s_mov_b32 s78, 0
	s_mov_b64 s[30:31], -1
	s_mov_b32 s59, 0.5
	s_waitcnt lgkmcnt(0)
	s_barrier
	s_branch .LBB0_473

; #define LAS __attribute__((address_space(3)))
; template <int L, int N, int NB> DEVQ void hyena_item(const Params& P, LAS unsigned char* lds, bf16* pT, float* zs, int d, size_t m0, const cf* specd, const float* cornerd) {
;     ...
;                 if (o == 0) {
;                     *(f32x4*)(zb + t0) = (f32x4){ya[0], ya[1], ya[2], ya[3]}; *(f32x4*)(zb + t0 + 4) = (f32x4){ya[4], ya[5], ya[6], ya[7]};
;                     *(f32x4*)(zb + L + t0) = (f32x4){yb[0], yb[1], yb[2], yb[3]}; *(f32x4*)(zb + L + t0 + 4) = (f32x4){yb[4], yb[5], yb[6], yb[7]};
; #pragma unroll
;                     for (int e = 0; e < 8; ++e) Xb[NB * swz(t0 + e)] = cf{ya[e], yb[e]};
;     ...
;                 for (int nb = 0; nb < NB; ++nb) { const float* zb = zs + nb * 2 * L; LAS float* cxb = cx + 64 * nb;
; #pragma unroll
;                     for (int e = 0; e < 8; ++e) { const int t = tid * 8 + e; cxb[t] = zb[t]; cxb[32 + t] = zb[L + t]; cxb[16 + t] = zb[N / 2 + t]; cxb[48 + t] = zb[L + N / 2 + t]; } } }
.LBB0_573:
	s_andn2_b64 vcc, exec, s[0:1]
	s_cbranch_vccnz .LBB0_496
	flat_store_dwordx4 v[58:59], v[8:11]
	flat_store_dwordx4 v[58:59], v[4:7] offset:16
	flat_store_dwordx4 v[56:57], v[0:3]
	flat_store_dwordx4 v[56:57], v[12:15] offset:16
	v_cmp_gt_i32_e64 s[80:81], 2, v116
	v_lshrrev_b32_e32 v16, 10, v116
	v_and_b32_e32 v17, 1, v116
	v_cmp_ne_u32_e64 s[82:83], 0, v16
	v_lshlrev_b32_e32 v17, 5, v17
	s_mov_b32 s28, 0x20000
	s_or_b64 s[80:81], s[80:81], s[82:83]
	v_cndmask_b32_e64 v16, 0, 64, s[82:83]
	v_add3_u32 v16, v17, v16, s28
	s_and_saveexec_b64 s[82:83], s[80:81]
	ds_write_b128 v16, v[8:11]
	ds_write_b128 v16, v[4:7] offset:16
	ds_write_b128 v16, v[0:3] offset:128
	ds_write_b128 v16, v[12:15] offset:144
	s_or_b64 exec, exec, s[82:83]
	v_mov_b32_e32 v17, v0
	v_mov_b32_e32 v0, v9
	ds_write_b64 v118, v[0:1]
	v_mov_b32_e32 v0, v10
	v_mov_b32_e32 v1, v2
	ds_write_b64 v119, v[0:1]
	v_mov_b32_e32 v0, v4
	v_mov_b32_e32 v1, v12
	v_mov_b32_e32 v16, v8
	v_mov_b32_e32 v2, v11
	ds_write_b64 v121, v[0:1]
	v_mov_b32_e32 v12, v5
	v_mov_b32_e32 v0, v6
	v_mov_b32_e32 v1, v14
	v_mov_b32_e32 v14, v7
	ds_write_b64 v117, v[16:17]
	ds_write_b64 v120, v[2:3]
	ds_write_b64 v122, v[12:13]
	ds_write_b64 v123, v[0:1]
	ds_write_b64 v124, v[14:15]
	s_branch .LBB0_496

; #define LAS __attribute__((address_space(3)))
; template <int L, int N, int NB> DEVQ void hyena_item(const Params& P, LAS unsigned char* lds, bf16* pT, float* zs, int d, size_t m0, const cf* specd, const float* cornerd) {
;     ...
;         if (o == 0) {
;             __syncthreads();
;             if (tid < 2) {
; #pragma unroll
;                 for (int nb = 0; nb < NB; ++nb) { const float* zb = zs + nb * 2 * L; LAS float* cxb = cx + 64 * nb;
; #pragma unroll
;                     for (int e = 0; e < 8; ++e) { const int t = tid * 8 + e; cxb[t] = zb[t]; cxb[32 + t] = zb[L + t]; cxb[16 + t] = zb[N / 2 + t]; cxb[48 + t] = zb[L + N / 2 + t]; } } }
;             __syncthreads();
.LBB0_579:
	s_or_b64 exec, exec, s[0:1]
	v_cmp_gt_i32_e32 vcc, 2, v41
	s_waitcnt lgkmcnt(0)
	s_barrier
	s_and_saveexec_b64 s[0:1], vcc
	s_cbranch_execz .LBB0_471
	s_branch .LBB0_471

; #define LAS __attribute__((address_space(3)))
; DEVQ unsigned pk2(float lo, float hi) { return f2bf(lo) | (f2bf(hi) << 16); }
; DEVQ void transpose_item(const float* W, int K, int N, bf16* WT, LAS float* scr, int item, int lane) {
;     const int nblk = N / 32, kb = item / nblk, nb = item % nblk, k0 = 64 * kb, n0 = 32 * nb;
; #pragma unroll 8
;     for (int i = 0; i < 32; ++i) { const int kk = 2 * i + (lane >> 5); scr[kk * 33 + (lane & 31)] = W[(size_t)(k0 + kk) * N + n0 + (lane & 31)]; }
;     asm volatile("s_waitcnt lgkmcnt(0)" ::: "memory");
;     const int c = lane & 7;
; #pragma unroll
;     for (int j = 0; j < 4; ++j) { const int n = (lane >> 3) + 8 * j; const LAS float* s = scr + (8 * c) * 33 + n;
;         v4u o; o.x = pk2(s[0 * 33], s[1 * 33]); o.y = pk2(s[2 * 33], s[3 * 33]); o.z = pk2(s[4 * 33], s[5 * 33]); o.w = pk2(s[6 * 33], s[7 * 33]);
;         *(v4u*)(WT + (size_t)(n0 + n) * K + k0 + 8 * c) = o; }
;     asm volatile("s_waitcnt lgkmcnt(0)" ::: "memory");
; }
.LBB0_738:
	v_lshl_add_u64 v[52:53], v[36:37], 0, s[0:1]
	flat_load_dword v64, v[52:53]
	v_lshl_add_u64 v[52:53], v[34:35], 0, s[0:1]
	flat_load_dword v65, v[52:53]
	v_lshl_add_u64 v[52:53], v[32:33], 0, s[0:1]
	flat_load_dword v66, v[52:53]
	v_lshl_add_u64 v[52:53], v[30:31], 0, s[0:1]
	flat_load_dword v67, v[52:53]
	v_lshl_add_u64 v[52:53], v[28:29], 0, s[0:1]
	flat_load_dword v68, v[52:53]
	v_lshl_add_u64 v[52:53], v[26:27], 0, s[0:1]
	flat_load_dword v69, v[52:53]
	v_lshl_add_u64 v[52:53], v[24:25], 0, s[0:1]
	flat_load_dword v70, v[52:53]
	v_lshl_add_u64 v[52:53], v[22:23], 0, s[0:1]
	s_add_u32 s0, s0, 0x10000
	s_addc_u32 s1, s1, 0
	s_cmp_lg_u32 s0, 0x40000
	flat_load_dword v71, v[52:53]
	s_waitcnt vmcnt(0) lgkmcnt(0)
	ds_write_b32 v51, v64
	ds_write_b32 v51, v65 offset:264
	ds_write_b32 v51, v66 offset:528
	ds_write_b32 v51, v67 offset:792
	ds_write_b32 v51, v68 offset:1056
	ds_write_b32 v51, v69 offset:1320
	ds_write_b32 v51, v70 offset:1584
	ds_write_b32 v51, v71 offset:1848
	v_add_u32_e32 v51, 0x840, v51
	s_cbranch_scc1 .LBB0_738
	s_waitcnt lgkmcnt(0)
	ds_read_b32 v22, v39
	ds_read_b32 v23, v39 offset:132
	ds_read_b32 v24, v39 offset:264
	ds_read_b32 v25, v39 offset:396
	ds_read_b32 v28, v39 offset:528
	ds_read_b32 v29, v39 offset:660
	ds_read_b32 v30, v39 offset:792
	ds_read_b32 v31, v39 offset:924
	s_waitcnt lgkmcnt(7)
	v_bfe_u32 v32, v22, 16, 1
	v_add3_u32 v22, v22, v32, s60
	s_waitcnt lgkmcnt(6)
	v_bfe_u32 v32, v23, 16, 1
	v_lshrrev_b32_e32 v22, 16, v22
	v_add3_u32 v23, v23, v32, s60
	v_and_or_b32 v22, v23, s61, v22
	s_waitcnt lgkmcnt(5)
	v_bfe_u32 v23, v24, 16, 1
	v_add3_u32 v23, v24, v23, s60
	s_waitcnt lgkmcnt(4)
	v_bfe_u32 v24, v25, 16, 1
	s_add_i32 s1, s12, 0xffffe300
	v_lshrrev_b32_e32 v23, 16, v23
	v_add3_u32 v24, v25, v24, s60
	s_lshr_b32 s14, s1, 11
	s_mov_b32 s15, s43
	v_and_or_b32 v23, v24, s61, v23
	s_waitcnt lgkmcnt(3)
	v_bfe_u32 v24, v28, 16, 1
	s_and_b32 s0, s2, 0x3e0
	s_lshl_b64 s[14:15], s[14:15], 23
	v_readlane_b32 s3, v255, 47
	v_add3_u32 v24, v28, v24, s60
	s_waitcnt lgkmcnt(2)
	v_bfe_u32 v25, v29, 16, 1
	s_add_u32 s3, s3, s14
	v_readlane_b32 s13, v255, 25
	v_lshrrev_b32_e32 v24, 16, v24
	v_add3_u32 v25, v29, v25, s60
	s_addc_u32 s13, s13, s15
	s_lshl_b32 s1, s1, 2
	v_and_or_b32 v24, v25, s61, v24
	s_waitcnt lgkmcnt(1)
	v_bfe_u32 v25, v30, 16, 1
	s_and_b32 s1, s1, 0x1f80
	v_add3_u32 v25, v30, v25, s60
	s_waitcnt lgkmcnt(0)
	v_bfe_u32 v28, v31, 16, 1
	s_add_u32 s14, s3, s1
	v_lshrrev_b32_e32 v25, 16, v25
	v_add3_u32 v28, v31, v28, s60
	s_addc_u32 s15, s13, 0
	v_lshlrev_b32_e32 v128, 1, v0
	v_and_or_b32 v25, v28, s61, v25
	v_or_b32_e32 v28, s0, v38
	v_lshl_add_u64 v[26:27], s[14:15], 0, v[128:129]
	v_lshlrev_b32_e32 v128, 13, v28
	v_lshl_add_u64 v[28:29], v[26:27], 0, v[128:129]
	flat_store_dwordx4 v[28:29], v[22:25]
	ds_read_b32 v22, v39 offset:32
	ds_read_b32 v23, v39 offset:164
	ds_read_b32 v24, v39 offset:296
	ds_read_b32 v25, v39 offset:428
	ds_read_b32 v28, v39 offset:560
	ds_read_b32 v29, v39 offset:692
	ds_read_b32 v30, v39 offset:824
	ds_read_b32 v31, v39 offset:956
	s_waitcnt lgkmcnt(0)
	v_bfe_u32 v32, v22, 16, 1
	v_add3_u32 v22, v22, v32, s60
	v_bfe_u32 v32, v23, 16, 1
	v_lshrrev_b32_e32 v22, 16, v22
	v_add3_u32 v23, v23, v32, s60
	v_and_or_b32 v22, v23, s61, v22
	v_bfe_u32 v23, v24, 16, 1
	v_add3_u32 v23, v24, v23, s60
	v_bfe_u32 v24, v25, 16, 1
	v_lshrrev_b32_e32 v23, 16, v23
	v_add3_u32 v24, v25, v24, s60
	v_and_or_b32 v23, v24, s61, v23
	v_bfe_u32 v24, v28, 16, 1
	v_add3_u32 v24, v28, v24, s60
	v_bfe_u32 v25, v29, 16, 1
	v_lshrrev_b32_e32 v24, 16, v24
	v_add3_u32 v25, v29, v25, s60
	v_and_or_b32 v24, v25, s61, v24
	v_bfe_u32 v25, v30, 16, 1
	v_add3_u32 v25, v30, v25, s60
	v_bfe_u32 v28, v31, 16, 1
	v_lshrrev_b32_e32 v25, 16, v25
	v_add3_u32 v28, v31, v28, s60
	v_and_or_b32 v25, v28, s61, v25
	v_or_b32_e32 v28, s0, v40
	v_lshlrev_b32_e32 v128, 13, v28
	v_lshl_add_u64 v[28:29], v[26:27], 0, v[128:129]
	flat_store_dwordx4 v[28:29], v[22:25]
	ds_read_b32 v22, v39 offset:64
	ds_read_b32 v23, v39 offset:196
	ds_read_b32 v24, v39 offset:328
	ds_read_b32 v25, v39 offset:460
	ds_read_b32 v28, v39 offset:592
	ds_read_b32 v29, v39 offset:724
	ds_read_b32 v30, v39 offset:856
	ds_read_b32 v31, v39 offset:988
	s_waitcnt lgkmcnt(0)
	v_bfe_u32 v32, v22, 16, 1
	v_add3_u32 v22, v22, v32, s60
	v_bfe_u32 v32, v23, 16, 1
	v_lshrrev_b32_e32 v22, 16, v22
	v_add3_u32 v23, v23, v32, s60
	v_and_or_b32 v22, v23, s61, v22
	v_bfe_u32 v23, v24, 16, 1
	v_add3_u32 v23, v24, v23, s60
	v_bfe_u32 v24, v25, 16, 1
	v_lshrrev_b32_e32 v23, 16, v23
	v_add3_u32 v24, v25, v24, s60
	v_and_or_b32 v23, v24, s61, v23
	v_bfe_u32 v24, v28, 16, 1
	v_add3_u32 v24, v28, v24, s60
	v_bfe_u32 v25, v29, 16, 1
	v_lshrrev_b32_e32 v24, 16, v24
	v_add3_u32 v25, v29, v25, s60
	v_and_or_b32 v24, v25, s61, v24
	v_bfe_u32 v25, v30, 16, 1
	v_add3_u32 v25, v30, v25, s60
	v_bfe_u32 v28, v31, 16, 1
	v_lshrrev_b32_e32 v25, 16, v25
	v_add3_u32 v28, v31, v28, s60
	v_and_or_b32 v25, v28, s61, v25
	v_or_b32_e32 v28, s0, v41
	v_lshlrev_b32_e32 v128, 13, v28
	v_lshl_add_u64 v[28:29], v[26:27], 0, v[128:129]
	flat_store_dwordx4 v[28:29], v[22:25]
	ds_read_b32 v22, v39 offset:96
	ds_read_b32 v23, v39 offset:228
	ds_read_b32 v24, v39 offset:360
	ds_read_b32 v25, v39 offset:492
	ds_read_b32 v28, v39 offset:624
	ds_read_b32 v29, v39 offset:756
	ds_read_b32 v30, v39 offset:888
	ds_read_b32 v31, v39 offset:1020
	s_waitcnt lgkmcnt(0)
	v_bfe_u32 v32, v22, 16, 1
	v_add3_u32 v22, v22, v32, s60
	v_bfe_u32 v32, v23, 16, 1
	v_lshrrev_b32_e32 v22, 16, v22
	v_add3_u32 v23, v23, v32, s60
	v_and_or_b32 v22, v23, s61, v22
	v_bfe_u32 v23, v24, 16, 1
	v_add3_u32 v23, v24, v23, s60
	v_bfe_u32 v24, v25, 16, 1
	v_lshrrev_b32_e32 v23, 16, v23
	v_add3_u32 v24, v25, v24, s60
	v_and_or_b32 v23, v24, s61, v23
	v_bfe_u32 v24, v28, 16, 1
	v_add3_u32 v24, v28, v24, s60
	v_bfe_u32 v25, v29, 16, 1
	v_lshrrev_b32_e32 v24, 16, v24
	v_add3_u32 v25, v29, v25, s60
	v_and_or_b32 v24, v25, s61, v24
	v_bfe_u32 v25, v30, 16, 1
	v_add3_u32 v25, v30, v25, s60
	v_bfe_u32 v28, v31, 16, 1
	v_lshrrev_b32_e32 v25, 16, v25
	v_add3_u32 v28, v31, v28, s60
	v_and_or_b32 v25, v28, s61, v25
	v_or_b32_e32 v28, s0, v42
	v_lshlrev_b32_e32 v128, 13, v28
	v_lshl_add_u64 v[26:27], v[26:27], 0, v[128:129]
	flat_store_dwordx4 v[26:27], v[22:25]
	s_waitcnt lgkmcnt(0)
	s_mov_b64 s[0:1], 0

; #define LAS __attribute__((address_space(3)))
; DEVQ unsigned pk2(float lo, float hi) { return f2bf(lo) | (f2bf(hi) << 16); }
; DEVQ void transpose_item(const float* W, int K, int N, bf16* WT, LAS float* scr, int item, int lane) {
;     const int nblk = N / 32, kb = item / nblk, nb = item % nblk, k0 = 64 * kb, n0 = 32 * nb;
; #pragma unroll 8
;     for (int i = 0; i < 32; ++i) { const int kk = 2 * i + (lane >> 5); scr[kk * 33 + (lane & 31)] = W[(size_t)(k0 + kk) * N + n0 + (lane & 31)]; }
;     asm volatile("s_waitcnt lgkmcnt(0)" ::: "memory");
;     const int c = lane & 7;
; #pragma unroll
;     for (int j = 0; j < 4; ++j) { const int n = (lane >> 3) + 8 * j; const LAS float* s = scr + (8 * c) * 33 + n;
;         v4u o; o.x = pk2(s[0 * 33], s[1 * 33]); o.y = pk2(s[2 * 33], s[3 * 33]); o.z = pk2(s[4 * 33], s[5 * 33]); o.w = pk2(s[6 * 33], s[7 * 33]);
;         *(v4u*)(WT + (size_t)(n0 + n) * K + k0 + 8 * c) = o; }
;     asm volatile("s_waitcnt lgkmcnt(0)" ::: "memory");
; }
.LBB0_742:
	v_lshl_add_u64 v[52:53], v[36:37], 0, s[0:1]
	flat_load_dword v64, v[52:53]
	v_lshl_add_u64 v[52:53], v[34:35], 0, s[0:1]
	flat_load_dword v65, v[52:53]
	v_lshl_add_u64 v[52:53], v[32:33], 0, s[0:1]
	flat_load_dword v66, v[52:53]
	v_lshl_add_u64 v[52:53], v[30:31], 0, s[0:1]
	flat_load_dword v67, v[52:53]
	v_lshl_add_u64 v[52:53], v[28:29], 0, s[0:1]
	flat_load_dword v68, v[52:53]
	v_lshl_add_u64 v[52:53], v[26:27], 0, s[0:1]
	flat_load_dword v69, v[52:53]
	v_lshl_add_u64 v[52:53], v[24:25], 0, s[0:1]
	flat_load_dword v70, v[52:53]
	v_lshl_add_u64 v[52:53], v[22:23], 0, s[0:1]
	s_add_u32 s0, s0, 0x40000
	s_addc_u32 s1, s1, 0
	s_cmp_lg_u32 s0, 0x100000
	flat_load_dword v71, v[52:53]
	s_waitcnt vmcnt(0) lgkmcnt(0)
	ds_write_b32 v51, v64
	ds_write_b32 v51, v65 offset:264
	ds_write_b32 v51, v66 offset:528
	ds_write_b32 v51, v67 offset:792
	ds_write_b32 v51, v68 offset:1056
	ds_write_b32 v51, v69 offset:1320
	ds_write_b32 v51, v70 offset:1584
	ds_write_b32 v51, v71 offset:1848
	v_add_u32_e32 v51, 0x840, v51
	s_cbranch_scc1 .LBB0_742
	s_waitcnt lgkmcnt(0)
	ds_read_b32 v22, v39
	ds_read_b32 v23, v39 offset:132
	ds_read_b32 v24, v39 offset:264
	ds_read_b32 v25, v39 offset:396
	ds_read_b32 v28, v39 offset:528
	ds_read_b32 v29, v39 offset:660
	ds_read_b32 v30, v39 offset:792
	ds_read_b32 v31, v39 offset:924
	s_waitcnt lgkmcnt(7)
	v_bfe_u32 v32, v22, 16, 1
	v_add3_u32 v22, v22, v32, s60
	s_waitcnt lgkmcnt(6)
	v_bfe_u32 v32, v23, 16, 1
	v_lshrrev_b32_e32 v22, 16, v22
	v_add3_u32 v23, v23, v32, s60
	v_and_or_b32 v22, v23, s61, v22
	s_waitcnt lgkmcnt(5)
	v_bfe_u32 v23, v24, 16, 1
	v_add3_u32 v23, v24, v23, s60
	s_waitcnt lgkmcnt(4)
	v_bfe_u32 v24, v25, 16, 1
	v_lshrrev_b32_e32 v23, 16, v23
	v_add3_u32 v24, v25, v24, s60
	s_add_i32 s1, s12, 0xfffff300
	v_and_or_b32 v23, v24, s61, v23
	s_waitcnt lgkmcnt(3)
	v_bfe_u32 v24, v28, 16, 1
	s_lshr_b32 s14, s1, 11
	s_mov_b32 s15, s43
	v_add3_u32 v24, v28, v24, s60
	s_waitcnt lgkmcnt(2)
	v_bfe_u32 v25, v29, 16, 1
	s_and_b32 s0, s2, 0xfe0
	s_lshl_b64 s[2:3], s[14:15], 23
	v_readlane_b32 s13, v255, 23
	v_lshrrev_b32_e32 v24, 16, v24
	v_add3_u32 v25, v29, v25, s60
	s_add_u32 s2, s13, s2
	v_readlane_b32 s13, v255, 24
	v_and_or_b32 v24, v25, s61, v24
	s_waitcnt lgkmcnt(1)
	v_bfe_u32 v25, v30, 16, 1
	s_addc_u32 s3, s13, s3
	s_and_b32 s1, s1, 0x780
	v_add3_u32 v25, v30, v25, s60
	s_waitcnt lgkmcnt(0)
	v_bfe_u32 v28, v31, 16, 1
	s_add_u32 s2, s2, s1
	v_lshrrev_b32_e32 v25, 16, v25
	v_add3_u32 v28, v31, v28, s60
	s_addc_u32 s3, s3, 0
	v_lshlrev_b32_e32 v128, 1, v0
	v_and_or_b32 v25, v28, s61, v25
	v_or_b32_e32 v28, s0, v38
	v_lshl_add_u64 v[26:27], s[2:3], 0, v[128:129]
	v_lshlrev_b32_e32 v128, 11, v28
	v_lshl_add_u64 v[28:29], v[26:27], 0, v[128:129]
	flat_store_dwordx4 v[28:29], v[22:25]
	ds_read_b32 v22, v39 offset:32
	ds_read_b32 v23, v39 offset:164
	ds_read_b32 v24, v39 offset:296
	ds_read_b32 v25, v39 offset:428
	ds_read_b32 v28, v39 offset:560
	ds_read_b32 v29, v39 offset:692
	ds_read_b32 v30, v39 offset:824
	ds_read_b32 v31, v39 offset:956
	s_waitcnt lgkmcnt(0)
	v_bfe_u32 v32, v22, 16, 1
	v_add3_u32 v22, v22, v32, s60
	v_bfe_u32 v32, v23, 16, 1
	v_lshrrev_b32_e32 v22, 16, v22
	v_add3_u32 v23, v23, v32, s60
	v_and_or_b32 v22, v23, s61, v22
	v_bfe_u32 v23, v24, 16, 1
	v_add3_u32 v23, v24, v23, s60
	v_bfe_u32 v24, v25, 16, 1
	v_lshrrev_b32_e32 v23, 16, v23
	v_add3_u32 v24, v25, v24, s60
	v_and_or_b32 v23, v24, s61, v23
	v_bfe_u32 v24, v28, 16, 1
	v_add3_u32 v24, v28, v24, s60
	v_bfe_u32 v25, v29, 16, 1
	v_lshrrev_b32_e32 v24, 16, v24
	v_add3_u32 v25, v29, v25, s60
	v_and_or_b32 v24, v25, s61, v24
	v_bfe_u32 v25, v30, 16, 1
	v_add3_u32 v25, v30, v25, s60
	v_bfe_u32 v28, v31, 16, 1
	v_lshrrev_b32_e32 v25, 16, v25
	v_add3_u32 v28, v31, v28, s60
	v_and_or_b32 v25, v28, s61, v25
	v_or_b32_e32 v28, s0, v40
	v_lshlrev_b32_e32 v128, 11, v28
	v_lshl_add_u64 v[28:29], v[26:27], 0, v[128:129]
	flat_store_dwordx4 v[28:29], v[22:25]
	ds_read_b32 v22, v39 offset:64
	ds_read_b32 v23, v39 offset:196
	ds_read_b32 v24, v39 offset:328
	ds_read_b32 v25, v39 offset:460
	ds_read_b32 v28, v39 offset:592
	ds_read_b32 v29, v39 offset:724
	ds_read_b32 v30, v39 offset:856
	ds_read_b32 v31, v39 offset:988
	s_waitcnt lgkmcnt(0)
	v_bfe_u32 v32, v22, 16, 1
	v_add3_u32 v22, v22, v32, s60
	v_bfe_u32 v32, v23, 16, 1
	v_lshrrev_b32_e32 v22, 16, v22
	v_add3_u32 v23, v23, v32, s60
	v_and_or_b32 v22, v23, s61, v22
	v_bfe_u32 v23, v24, 16, 1
	v_add3_u32 v23, v24, v23, s60
	v_bfe_u32 v24, v25, 16, 1
	v_lshrrev_b32_e32 v23, 16, v23
	v_add3_u32 v24, v25, v24, s60
	v_and_or_b32 v23, v24, s61, v23
	v_bfe_u32 v24, v28, 16, 1
	v_add3_u32 v24, v28, v24, s60
	v_bfe_u32 v25, v29, 16, 1
	v_lshrrev_b32_e32 v24, 16, v24
	v_add3_u32 v25, v29, v25, s60
	v_and_or_b32 v24, v25, s61, v24
	v_bfe_u32 v25, v30, 16, 1
	v_add3_u32 v25, v30, v25, s60
	v_bfe_u32 v28, v31, 16, 1
	v_lshrrev_b32_e32 v25, 16, v25
	v_add3_u32 v28, v31, v28, s60
	v_and_or_b32 v25, v28, s61, v25
	v_or_b32_e32 v28, s0, v41
	v_lshlrev_b32_e32 v128, 11, v28
	v_lshl_add_u64 v[28:29], v[26:27], 0, v[128:129]
	flat_store_dwordx4 v[28:29], v[22:25]
	ds_read_b32 v22, v39 offset:96
	ds_read_b32 v23, v39 offset:228
	ds_read_b32 v24, v39 offset:360
	ds_read_b32 v25, v39 offset:492
	ds_read_b32 v28, v39 offset:624
	ds_read_b32 v29, v39 offset:756
	ds_read_b32 v30, v39 offset:888
	ds_read_b32 v31, v39 offset:1020
	s_waitcnt lgkmcnt(0)
	v_bfe_u32 v32, v22, 16, 1
	v_add3_u32 v22, v22, v32, s60
	v_bfe_u32 v32, v23, 16, 1
	v_lshrrev_b32_e32 v22, 16, v22
	v_add3_u32 v23, v23, v32, s60
	v_and_or_b32 v22, v23, s61, v22
	v_bfe_u32 v23, v24, 16, 1
	v_add3_u32 v23, v24, v23, s60
	v_bfe_u32 v24, v25, 16, 1
	v_lshrrev_b32_e32 v23, 16, v23
	v_add3_u32 v24, v25, v24, s60
	v_and_or_b32 v23, v24, s61, v23
	v_bfe_u32 v24, v28, 16, 1
	v_add3_u32 v24, v28, v24, s60
	v_bfe_u32 v25, v29, 16, 1
	v_lshrrev_b32_e32 v24, 16, v24
	v_add3_u32 v25, v29, v25, s60
	v_and_or_b32 v24, v25, s61, v24
	v_bfe_u32 v25, v30, 16, 1
	v_add3_u32 v25, v30, v25, s60
	v_bfe_u32 v28, v31, 16, 1
	v_lshrrev_b32_e32 v25, 16, v25
	v_add3_u32 v28, v31, v28, s60
	v_and_or_b32 v25, v28, s61, v25
	v_or_b32_e32 v28, s0, v42
	v_lshlrev_b32_e32 v128, 11, v28
	v_lshl_add_u64 v[26:27], v[26:27], 0, v[128:129]
	flat_store_dwordx4 v[26:27], v[22:25]
	s_waitcnt lgkmcnt(0)

; #define LAS __attribute__((address_space(3)))
; DEVQ unsigned pk2(float lo, float hi) { return f2bf(lo) | (f2bf(hi) << 16); }
; DEVQ void transpose_item(const float* W, int K, int N, bf16* WT, LAS float* scr, int item, int lane) {
;     const int nblk = N / 32, kb = item / nblk, nb = item % nblk, k0 = 64 * kb, n0 = 32 * nb;
; #pragma unroll 8
;     for (int i = 0; i < 32; ++i) { const int kk = 2 * i + (lane >> 5); scr[kk * 33 + (lane & 31)] = W[(size_t)(k0 + kk) * N + n0 + (lane & 31)]; }
;     asm volatile("s_waitcnt lgkmcnt(0)" ::: "memory");
;     const int c = lane & 7;
; #pragma unroll
;     for (int j = 0; j < 4; ++j) { const int n = (lane >> 3) + 8 * j; const LAS float* s = scr + (8 * c) * 33 + n;
;         v4u o; o.x = pk2(s[0 * 33], s[1 * 33]); o.y = pk2(s[2 * 33], s[3 * 33]); o.z = pk2(s[4 * 33], s[5 * 33]); o.w = pk2(s[6 * 33], s[7 * 33]);
;         *(v4u*)(WT + (size_t)(n0 + n) * K + k0 + 8 * c) = o; }
;     asm volatile("s_waitcnt lgkmcnt(0)" ::: "memory");
; }
.LBB0_747:
	v_lshl_add_u64 v[52:53], v[36:37], 0, s[0:1]
	flat_load_dword v64, v[52:53]
	v_lshl_add_u64 v[52:53], v[34:35], 0, s[0:1]
	flat_load_dword v65, v[52:53]
	v_lshl_add_u64 v[52:53], v[32:33], 0, s[0:1]
	flat_load_dword v66, v[52:53]
	v_lshl_add_u64 v[52:53], v[30:31], 0, s[0:1]
	flat_load_dword v67, v[52:53]
	v_lshl_add_u64 v[52:53], v[28:29], 0, s[0:1]
	flat_load_dword v68, v[52:53]
	v_lshl_add_u64 v[52:53], v[26:27], 0, s[0:1]
	flat_load_dword v69, v[52:53]
	v_lshl_add_u64 v[52:53], v[24:25], 0, s[0:1]
	flat_load_dword v70, v[52:53]
	v_lshl_add_u64 v[52:53], v[22:23], 0, s[0:1]
	s_add_u32 s0, s0, 0x10000
	s_addc_u32 s1, s1, 0
	s_cmp_lg_u32 s0, 0x40000
	flat_load_dword v71, v[52:53]
	s_waitcnt vmcnt(0) lgkmcnt(0)
	ds_write_b32 v51, v64
	ds_write_b32 v51, v65 offset:264
	ds_write_b32 v51, v66 offset:528
	ds_write_b32 v51, v67 offset:792
	ds_write_b32 v51, v68 offset:1056
	ds_write_b32 v51, v69 offset:1320
	ds_write_b32 v51, v70 offset:1584
	ds_write_b32 v51, v71 offset:1848
	v_add_u32_e32 v51, 0x840, v51
	s_cbranch_scc1 .LBB0_747
	s_waitcnt lgkmcnt(0)
	ds_read_b32 v22, v39
	ds_read_b32 v23, v39 offset:132
	ds_read_b32 v24, v39 offset:264
	ds_read_b32 v25, v39 offset:396
	ds_read_b32 v28, v39 offset:528
	ds_read_b32 v29, v39 offset:660
	ds_read_b32 v30, v39 offset:792
	ds_read_b32 v31, v39 offset:924
	s_waitcnt lgkmcnt(7)
	v_bfe_u32 v32, v22, 16, 1
	v_add3_u32 v22, v22, v32, s60
	s_waitcnt lgkmcnt(6)
	v_bfe_u32 v32, v23, 16, 1
	v_lshrrev_b32_e32 v22, 16, v22
	v_add3_u32 v23, v23, v32, s60
	v_and_or_b32 v22, v23, s61, v22
	s_waitcnt lgkmcnt(5)
	v_bfe_u32 v23, v24, 16, 1
	v_add3_u32 v23, v24, v23, s60
	s_waitcnt lgkmcnt(4)
	v_bfe_u32 v24, v25, 16, 1
	v_lshrrev_b32_e32 v23, 16, v23
	v_add3_u32 v24, v25, v24, s60
	v_and_or_b32 v23, v24, s61, v23
	s_waitcnt lgkmcnt(3)
	v_bfe_u32 v24, v28, 16, 1
	v_add3_u32 v24, v28, v24, s60
	s_waitcnt lgkmcnt(2)
	v_bfe_u32 v25, v29, 16, 1
	s_lshl_b32 s0, s12, 1
	v_lshrrev_b32_e32 v24, 16, v24
	v_add3_u32 v25, v29, v25, s60
	s_add_i32 s0, s0, 0x1ea00
	v_and_or_b32 v24, v25, s61, v24
	s_waitcnt lgkmcnt(1)
	v_bfe_u32 v25, v30, 16, 1
	s_and_b32 s1, s0, 0x1ffc0
	s_lshl_b32 s0, s12, 5
	v_add3_u32 v25, v30, v25, s60
	s_waitcnt lgkmcnt(0)
	v_bfe_u32 v28, v31, 16, 1
	s_and_b32 s0, s0, 0x3e0
	v_lshrrev_b32_e32 v25, 16, v25
	v_add3_u32 v28, v31, v28, s60
	s_lshl_b32 s2, s1, 1
	s_mov_b32 s3, s43
	v_and_or_b32 v25, v28, s61, v25
	v_or_b32_e32 v28, s0, v38
	v_lshl_add_u64 v[26:27], v[2:3], 0, s[2:3]
	v_lshlrev_b32_e32 v128, 11, v28
	v_lshl_add_u64 v[28:29], v[26:27], 0, v[128:129]
	flat_store_dwordx4 v[28:29], v[22:25]
	ds_read_b32 v22, v39 offset:32
	ds_read_b32 v23, v39 offset:164
	ds_read_b32 v24, v39 offset:296
	ds_read_b32 v25, v39 offset:428
	ds_read_b32 v28, v39 offset:560
	ds_read_b32 v29, v39 offset:692
	ds_read_b32 v30, v39 offset:824
	ds_read_b32 v31, v39 offset:956
	s_waitcnt lgkmcnt(0)
	v_bfe_u32 v32, v22, 16, 1
	v_add3_u32 v22, v22, v32, s60
	v_bfe_u32 v32, v23, 16, 1
	v_lshrrev_b32_e32 v22, 16, v22
	v_add3_u32 v23, v23, v32, s60
	v_and_or_b32 v22, v23, s61, v22
	v_bfe_u32 v23, v24, 16, 1
	v_add3_u32 v23, v24, v23, s60
	v_bfe_u32 v24, v25, 16, 1
	v_lshrrev_b32_e32 v23, 16, v23
	v_add3_u32 v24, v25, v24, s60
	v_and_or_b32 v23, v24, s61, v23
	v_bfe_u32 v24, v28, 16, 1
	v_add3_u32 v24, v28, v24, s60
	v_bfe_u32 v25, v29, 16, 1
	v_lshrrev_b32_e32 v24, 16, v24
	v_add3_u32 v25, v29, v25, s60
	v_and_or_b32 v24, v25, s61, v24
	v_bfe_u32 v25, v30, 16, 1
	v_add3_u32 v25, v30, v25, s60
	v_bfe_u32 v28, v31, 16, 1
	v_lshrrev_b32_e32 v25, 16, v25
	v_add3_u32 v28, v31, v28, s60
	v_and_or_b32 v25, v28, s61, v25
	v_or_b32_e32 v28, s0, v40
	v_lshlrev_b32_e32 v128, 11, v28
	v_lshl_add_u64 v[28:29], v[26:27], 0, v[128:129]
	flat_store_dwordx4 v[28:29], v[22:25]
	ds_read_b32 v22, v39 offset:64
	ds_read_b32 v23, v39 offset:196
	ds_read_b32 v24, v39 offset:328
	ds_read_b32 v25, v39 offset:460
	ds_read_b32 v28, v39 offset:592
	ds_read_b32 v29, v39 offset:724
	ds_read_b32 v30, v39 offset:856
	ds_read_b32 v31, v39 offset:988
	s_waitcnt lgkmcnt(0)
	v_bfe_u32 v32, v22, 16, 1
	v_add3_u32 v22, v22, v32, s60
	v_bfe_u32 v32, v23, 16, 1
	v_lshrrev_b32_e32 v22, 16, v22
	v_add3_u32 v23, v23, v32, s60
	v_and_or_b32 v22, v23, s61, v22
	v_bfe_u32 v23, v24, 16, 1
	v_add3_u32 v23, v24, v23, s60
	v_bfe_u32 v24, v25, 16, 1
	v_lshrrev_b32_e32 v23, 16, v23
	v_add3_u32 v24, v25, v24, s60
	v_and_or_b32 v23, v24, s61, v23
	v_bfe_u32 v24, v28, 16, 1
	v_add3_u32 v24, v28, v24, s60
	v_bfe_u32 v25, v29, 16, 1
	v_lshrrev_b32_e32 v24, 16, v24
	v_add3_u32 v25, v29, v25, s60
	v_and_or_b32 v24, v25, s61, v24
	v_bfe_u32 v25, v30, 16, 1
	v_add3_u32 v25, v30, v25, s60
	v_bfe_u32 v28, v31, 16, 1
	v_lshrrev_b32_e32 v25, 16, v25
	v_add3_u32 v28, v31, v28, s60
	v_and_or_b32 v25, v28, s61, v25
	v_or_b32_e32 v28, s0, v41
	v_lshlrev_b32_e32 v128, 11, v28
	v_lshl_add_u64 v[28:29], v[26:27], 0, v[128:129]
	flat_store_dwordx4 v[28:29], v[22:25]
	ds_read_b32 v22, v39 offset:96
	ds_read_b32 v23, v39 offset:228
	ds_read_b32 v24, v39 offset:360
	ds_read_b32 v25, v39 offset:492
	ds_read_b32 v28, v39 offset:624
	ds_read_b32 v29, v39 offset:756
	ds_read_b32 v30, v39 offset:888
	ds_read_b32 v31, v39 offset:1020
	s_waitcnt lgkmcnt(0)
	v_bfe_u32 v32, v22, 16, 1
	v_add3_u32 v22, v22, v32, s60
	v_bfe_u32 v32, v23, 16, 1
	v_lshrrev_b32_e32 v22, 16, v22
	v_add3_u32 v23, v23, v32, s60
	v_and_or_b32 v22, v23, s61, v22
	v_bfe_u32 v23, v24, 16, 1
	v_add3_u32 v23, v24, v23, s60
	v_bfe_u32 v24, v25, 16, 1
	v_lshrrev_b32_e32 v23, 16, v23
	v_add3_u32 v24, v25, v24, s60
	v_and_or_b32 v23, v24, s61, v23
	v_bfe_u32 v24, v28, 16, 1
	v_add3_u32 v24, v28, v24, s60
	v_bfe_u32 v25, v29, 16, 1
	v_lshrrev_b32_e32 v24, 16, v24
	v_add3_u32 v25, v29, v25, s60
	v_and_or_b32 v24, v25, s61, v24
	v_bfe_u32 v25, v30, 16, 1
	v_add3_u32 v25, v30, v25, s60
	v_bfe_u32 v28, v31, 16, 1
	v_lshrrev_b32_e32 v25, 16, v25
	v_add3_u32 v28, v31, v28, s60
	v_and_or_b32 v25, v28, s61, v25
	v_or_b32_e32 v28, s0, v42
	v_lshlrev_b32_e32 v128, 11, v28
	v_lshl_add_u64 v[26:27], v[26:27], 0, v[128:129]
	flat_store_dwordx4 v[26:27], v[22:25]
	s_waitcnt lgkmcnt(0)

; #define LAS __attribute__((address_space(3)))
; DEVQ unsigned pk2(float lo, float hi) { return f2bf(lo) | (f2bf(hi) << 16); }
; DEVQ void transpose_item(const float* W, int K, int N, bf16* WT, LAS float* scr, int item, int lane) {
;     const int nblk = N / 32, kb = item / nblk, nb = item % nblk, k0 = 64 * kb, n0 = 32 * nb;
; #pragma unroll 8
;     for (int i = 0; i < 32; ++i) { const int kk = 2 * i + (lane >> 5); scr[kk * 33 + (lane & 31)] = W[(size_t)(k0 + kk) * N + n0 + (lane & 31)]; }
;     asm volatile("s_waitcnt lgkmcnt(0)" ::: "memory");
;     const int c = lane & 7;
; #pragma unroll
;     for (int j = 0; j < 4; ++j) { const int n = (lane >> 3) + 8 * j; const LAS float* s = scr + (8 * c) * 33 + n;
;         v4u o; o.x = pk2(s[0 * 33], s[1 * 33]); o.y = pk2(s[2 * 33], s[3 * 33]); o.z = pk2(s[4 * 33], s[5 * 33]); o.w = pk2(s[6 * 33], s[7 * 33]);
;         *(v4u*)(WT + (size_t)(n0 + n) * K + k0 + 8 * c) = o; }
;     asm volatile("s_waitcnt lgkmcnt(0)" ::: "memory");
; }
.LBB0_752:
	v_lshl_add_u64 v[52:53], v[36:37], 0, s[0:1]
	flat_load_dword v64, v[52:53]
	v_lshl_add_u64 v[52:53], v[34:35], 0, s[0:1]
	flat_load_dword v65, v[52:53]
	v_lshl_add_u64 v[52:53], v[32:33], 0, s[0:1]
	flat_load_dword v66, v[52:53]
	v_lshl_add_u64 v[52:53], v[30:31], 0, s[0:1]
	flat_load_dword v67, v[52:53]
	v_lshl_add_u64 v[52:53], v[28:29], 0, s[0:1]
	flat_load_dword v68, v[52:53]
	v_lshl_add_u64 v[52:53], v[26:27], 0, s[0:1]
	flat_load_dword v69, v[52:53]
	v_lshl_add_u64 v[52:53], v[24:25], 0, s[0:1]
	flat_load_dword v70, v[52:53]
	v_lshl_add_u64 v[52:53], v[22:23], 0, s[0:1]
	s_add_u32 s0, s0, 0x18000
	s_addc_u32 s1, s1, 0
	s_cmp_lg_u32 s0, 0x60000
	flat_load_dword v71, v[52:53]
	s_waitcnt vmcnt(0) lgkmcnt(0)
	ds_write_b32 v51, v64
	ds_write_b32 v51, v65 offset:264
	ds_write_b32 v51, v66 offset:528
	ds_write_b32 v51, v67 offset:792
	ds_write_b32 v51, v68 offset:1056
	ds_write_b32 v51, v69 offset:1320
	ds_write_b32 v51, v70 offset:1584
	ds_write_b32 v51, v71 offset:1848
	v_add_u32_e32 v51, 0x840, v51
	s_cbranch_scc1 .LBB0_752
	s_waitcnt lgkmcnt(0)
	ds_read_b32 v22, v39
	ds_read_b32 v23, v39 offset:132
	ds_read_b32 v24, v39 offset:264
	ds_read_b32 v25, v39 offset:396
	ds_read_b32 v28, v39 offset:528
	ds_read_b32 v29, v39 offset:660
	ds_read_b32 v30, v39 offset:792
	ds_read_b32 v31, v39 offset:924
	s_waitcnt lgkmcnt(7)
	v_bfe_u32 v32, v22, 16, 1
	v_add3_u32 v22, v22, v32, s60
	s_waitcnt lgkmcnt(6)
	v_bfe_u32 v32, v23, 16, 1
	v_lshrrev_b32_e32 v22, 16, v22
	v_add3_u32 v23, v23, v32, s60
	v_and_or_b32 v22, v23, s61, v22
	s_waitcnt lgkmcnt(5)
	v_bfe_u32 v23, v24, 16, 1
	v_add3_u32 v23, v24, v23, s60
	s_waitcnt lgkmcnt(4)
	v_bfe_u32 v24, v25, 16, 1
	v_lshrrev_b32_e32 v23, 16, v23
	v_add3_u32 v24, v25, v24, s60
	v_and_or_b32 v23, v24, s61, v23
	s_waitcnt lgkmcnt(3)
	v_bfe_u32 v24, v28, 16, 1
	v_add3_u32 v24, v28, v24, s60
	s_waitcnt lgkmcnt(2)
	v_bfe_u32 v25, v29, 16, 1
	v_lshrrev_b32_e32 v24, 16, v24
	v_add3_u32 v25, v29, v25, s60
	v_and_or_b32 v24, v25, s61, v24
	s_waitcnt lgkmcnt(1)
	v_bfe_u32 v25, v30, 16, 1
	v_add3_u32 v25, v30, v25, s60
	s_waitcnt lgkmcnt(0)
	v_bfe_u32 v28, v31, 16, 1
	s_and_b32 s0, 0xffff, s3
	v_lshrrev_b32_e32 v25, 16, v25
	v_add3_u32 v28, v31, v28, s60
	s_lshl_b32 s2, s2, 1
	s_mov_b32 s3, s43
	v_and_or_b32 v25, v28, s61, v25
	v_or_b32_e32 v28, s0, v38
	v_lshl_add_u64 v[26:27], v[4:5], 0, s[2:3]
	v_lshlrev_b32_e32 v128, 11, v28
	v_lshl_add_u64 v[28:29], v[26:27], 0, v[128:129]
	flat_store_dwordx4 v[28:29], v[22:25]
	ds_read_b32 v22, v39 offset:32
	ds_read_b32 v23, v39 offset:164
	ds_read_b32 v24, v39 offset:296
	ds_read_b32 v25, v39 offset:428
	ds_read_b32 v28, v39 offset:560
	ds_read_b32 v29, v39 offset:692
	ds_read_b32 v30, v39 offset:824
	ds_read_b32 v31, v39 offset:956
	s_waitcnt lgkmcnt(0)
	v_bfe_u32 v32, v22, 16, 1
	v_add3_u32 v22, v22, v32, s60
	v_bfe_u32 v32, v23, 16, 1
	v_lshrrev_b32_e32 v22, 16, v22
	v_add3_u32 v23, v23, v32, s60
	v_and_or_b32 v22, v23, s61, v22
	v_bfe_u32 v23, v24, 16, 1
	v_add3_u32 v23, v24, v23, s60
	v_bfe_u32 v24, v25, 16, 1
	v_lshrrev_b32_e32 v23, 16, v23
	v_add3_u32 v24, v25, v24, s60
	v_and_or_b32 v23, v24, s61, v23
	v_bfe_u32 v24, v28, 16, 1
	v_add3_u32 v24, v28, v24, s60
	v_bfe_u32 v25, v29, 16, 1
	v_lshrrev_b32_e32 v24, 16, v24
	v_add3_u32 v25, v29, v25, s60
	v_and_or_b32 v24, v25, s61, v24
	v_bfe_u32 v25, v30, 16, 1
	v_add3_u32 v25, v30, v25, s60
	v_bfe_u32 v28, v31, 16, 1
	v_lshrrev_b32_e32 v25, 16, v25
	v_add3_u32 v28, v31, v28, s60
	v_and_or_b32 v25, v28, s61, v25
	v_or_b32_e32 v28, s0, v40
	v_lshlrev_b32_e32 v128, 11, v28
	v_lshl_add_u64 v[28:29], v[26:27], 0, v[128:129]
	flat_store_dwordx4 v[28:29], v[22:25]
	ds_read_b32 v22, v39 offset:64
	ds_read_b32 v23, v39 offset:196
	ds_read_b32 v24, v39 offset:328
	ds_read_b32 v25, v39 offset:460
	ds_read_b32 v28, v39 offset:592
	ds_read_b32 v29, v39 offset:724
	ds_read_b32 v30, v39 offset:856
	ds_read_b32 v31, v39 offset:988
	s_waitcnt lgkmcnt(0)
	v_bfe_u32 v32, v22, 16, 1
	v_add3_u32 v22, v22, v32, s60
	v_bfe_u32 v32, v23, 16, 1
	v_lshrrev_b32_e32 v22, 16, v22
	v_add3_u32 v23, v23, v32, s60
	v_and_or_b32 v22, v23, s61, v22
	v_bfe_u32 v23, v24, 16, 1
	v_add3_u32 v23, v24, v23, s60
	v_bfe_u32 v24, v25, 16, 1
	v_lshrrev_b32_e32 v23, 16, v23
	v_add3_u32 v24, v25, v24, s60
	v_and_or_b32 v23, v24, s61, v23
	v_bfe_u32 v24, v28, 16, 1
	v_add3_u32 v24, v28, v24, s60
	v_bfe_u32 v25, v29, 16, 1
	v_lshrrev_b32_e32 v24, 16, v24
	v_add3_u32 v25, v29, v25, s60
	v_and_or_b32 v24, v25, s61, v24
	v_bfe_u32 v25, v30, 16, 1
	v_add3_u32 v25, v30, v25, s60
	v_bfe_u32 v28, v31, 16, 1
	v_lshrrev_b32_e32 v25, 16, v25
	v_add3_u32 v28, v31, v28, s60
	v_and_or_b32 v25, v28, s61, v25
	v_or_b32_e32 v28, s0, v41
	v_lshlrev_b32_e32 v128, 11, v28
	v_lshl_add_u64 v[28:29], v[26:27], 0, v[128:129]
	flat_store_dwordx4 v[28:29], v[22:25]
	ds_read_b32 v22, v39 offset:96
	ds_read_b32 v23, v39 offset:228
	ds_read_b32 v24, v39 offset:360
	ds_read_b32 v25, v39 offset:492
	ds_read_b32 v28, v39 offset:624
	ds_read_b32 v29, v39 offset:756
	ds_read_b32 v30, v39 offset:888
	ds_read_b32 v31, v39 offset:1020
	s_waitcnt lgkmcnt(0)
	v_bfe_u32 v32, v22, 16, 1
	v_add3_u32 v22, v22, v32, s60
	v_bfe_u32 v32, v23, 16, 1
	v_lshrrev_b32_e32 v22, 16, v22
	v_add3_u32 v23, v23, v32, s60
	v_and_or_b32 v22, v23, s61, v22
	v_bfe_u32 v23, v24, 16, 1
	v_add3_u32 v23, v24, v23, s60
	v_bfe_u32 v24, v25, 16, 1
	v_lshrrev_b32_e32 v23, 16, v23
	v_add3_u32 v24, v25, v24, s60
	v_and_or_b32 v23, v24, s61, v23
	v_bfe_u32 v24, v28, 16, 1
	v_add3_u32 v24, v28, v24, s60
	v_bfe_u32 v25, v29, 16, 1
	v_lshrrev_b32_e32 v24, 16, v24
	v_add3_u32 v25, v29, v25, s60
	v_and_or_b32 v24, v25, s61, v24
	v_bfe_u32 v25, v30, 16, 1
	v_add3_u32 v25, v30, v25, s60
	v_bfe_u32 v28, v31, 16, 1
	v_lshrrev_b32_e32 v25, 16, v25
	v_add3_u32 v28, v31, v28, s60
	v_and_or_b32 v25, v28, s61, v25
	v_or_b32_e32 v28, s0, v42
	v_lshlrev_b32_e32 v128, 11, v28
	v_lshl_add_u64 v[26:27], v[26:27], 0, v[128:129]
	flat_store_dwordx4 v[26:27], v[22:25]
	s_waitcnt lgkmcnt(0)

; #define LAS __attribute__((address_space(3)))
; DEVQ unsigned pk2(float lo, float hi) { return f2bf(lo) | (f2bf(hi) << 16); }
; DEVQ void transpose_item(const float* W, int K, int N, bf16* WT, LAS float* scr, int item, int lane) {
;     const int nblk = N / 32, kb = item / nblk, nb = item % nblk, k0 = 64 * kb, n0 = 32 * nb;
; #pragma unroll 8
;     for (int i = 0; i < 32; ++i) { const int kk = 2 * i + (lane >> 5); scr[kk * 33 + (lane & 31)] = W[(size_t)(k0 + kk) * N + n0 + (lane & 31)]; }
;     asm volatile("s_waitcnt lgkmcnt(0)" ::: "memory");
;     const int c = lane & 7;
; #pragma unroll
;     for (int j = 0; j < 4; ++j) { const int n = (lane >> 3) + 8 * j; const LAS float* s = scr + (8 * c) * 33 + n;
;         v4u o; o.x = pk2(s[0 * 33], s[1 * 33]); o.y = pk2(s[2 * 33], s[3 * 33]); o.z = pk2(s[4 * 33], s[5 * 33]); o.w = pk2(s[6 * 33], s[7 * 33]);
;         *(v4u*)(WT + (size_t)(n0 + n) * K + k0 + 8 * c) = o; }
;     asm volatile("s_waitcnt lgkmcnt(0)" ::: "memory");
; }
.LBB0_757:
	v_lshl_add_u64 v[52:53], v[36:37], 0, s[0:1]
	flat_load_dword v64, v[52:53]
	v_lshl_add_u64 v[52:53], v[34:35], 0, s[0:1]
	flat_load_dword v65, v[52:53]
	v_lshl_add_u64 v[52:53], v[32:33], 0, s[0:1]
	flat_load_dword v66, v[52:53]
	v_lshl_add_u64 v[52:53], v[30:31], 0, s[0:1]
	flat_load_dword v67, v[52:53]
	v_lshl_add_u64 v[52:53], v[28:29], 0, s[0:1]
	flat_load_dword v68, v[52:53]
	v_lshl_add_u64 v[52:53], v[26:27], 0, s[0:1]
	flat_load_dword v69, v[52:53]
	v_lshl_add_u64 v[52:53], v[24:25], 0, s[0:1]
	flat_load_dword v70, v[52:53]
	v_lshl_add_u64 v[52:53], v[22:23], 0, s[0:1]
	s_add_u32 s0, s0, 0x10000
	s_addc_u32 s1, s1, 0
	s_cmp_lg_u32 s0, 0x40000
	flat_load_dword v71, v[52:53]
	s_waitcnt vmcnt(0) lgkmcnt(0)
	ds_write_b32 v51, v64
	ds_write_b32 v51, v65 offset:264
	ds_write_b32 v51, v66 offset:528
	ds_write_b32 v51, v67 offset:792
	ds_write_b32 v51, v68 offset:1056
	ds_write_b32 v51, v69 offset:1320
	ds_write_b32 v51, v70 offset:1584
	ds_write_b32 v51, v71 offset:1848
	v_add_u32_e32 v51, 0x840, v51
	s_cbranch_scc1 .LBB0_757
	s_waitcnt lgkmcnt(0)
	ds_read_b32 v22, v39
	ds_read_b32 v23, v39 offset:132
	ds_read_b32 v24, v39 offset:264
	ds_read_b32 v25, v39 offset:396
	ds_read_b32 v28, v39 offset:528
	ds_read_b32 v29, v39 offset:660
	ds_read_b32 v30, v39 offset:792
	ds_read_b32 v31, v39 offset:924
	s_waitcnt lgkmcnt(7)
	v_bfe_u32 v32, v22, 16, 1
	v_add3_u32 v22, v22, v32, s60
	s_waitcnt lgkmcnt(6)
	v_bfe_u32 v32, v23, 16, 1
	v_lshrrev_b32_e32 v22, 16, v22
	v_add3_u32 v23, v23, v32, s60
	v_and_or_b32 v22, v23, s61, v22
	s_waitcnt lgkmcnt(5)
	v_bfe_u32 v23, v24, 16, 1
	v_add3_u32 v23, v24, v23, s60
	s_waitcnt lgkmcnt(4)
	v_bfe_u32 v24, v25, 16, 1
	v_lshrrev_b32_e32 v23, 16, v23
	v_add3_u32 v24, v25, v24, s60
	v_and_or_b32 v23, v24, s61, v23
	s_waitcnt lgkmcnt(3)
	v_bfe_u32 v24, v28, 16, 1
	v_add3_u32 v24, v28, v24, s60
	s_waitcnt lgkmcnt(2)
	v_bfe_u32 v25, v29, 16, 1
	s_lshl_b32 s0, s12, 1
	v_lshrrev_b32_e32 v24, 16, v24
	v_add3_u32 v25, v29, v25, s60
	s_add_i32 s0, s0, 0x1f400
	v_and_or_b32 v24, v25, s61, v24
	s_waitcnt lgkmcnt(1)
	v_bfe_u32 v25, v30, 16, 1
	s_and_b32 s1, s0, 0x1ffc0
	s_lshl_b32 s0, s12, 5
	v_add3_u32 v25, v30, v25, s60
	s_waitcnt lgkmcnt(0)
	v_bfe_u32 v28, v31, 16, 1
	s_and_b32 s0, s0, 0x3e0
	v_lshrrev_b32_e32 v25, 16, v25
	v_add3_u32 v28, v31, v28, s60
	s_lshl_b32 s42, s1, 1
	v_and_or_b32 v25, v28, s61, v25
	v_or_b32_e32 v28, s0, v38
	v_lshl_add_u64 v[26:27], v[6:7], 0, s[42:43]
	v_lshlrev_b32_e32 v128, 11, v28
	v_lshl_add_u64 v[28:29], v[26:27], 0, v[128:129]
	flat_store_dwordx4 v[28:29], v[22:25]
	ds_read_b32 v22, v39 offset:32
	ds_read_b32 v23, v39 offset:164
	ds_read_b32 v24, v39 offset:296
	ds_read_b32 v25, v39 offset:428
	ds_read_b32 v28, v39 offset:560
	ds_read_b32 v29, v39 offset:692
	ds_read_b32 v30, v39 offset:824
	ds_read_b32 v31, v39 offset:956
	s_waitcnt lgkmcnt(0)
	v_bfe_u32 v32, v22, 16, 1
	v_add3_u32 v22, v22, v32, s60
	v_bfe_u32 v32, v23, 16, 1
	v_lshrrev_b32_e32 v22, 16, v22
	v_add3_u32 v23, v23, v32, s60
	v_and_or_b32 v22, v23, s61, v22
	v_bfe_u32 v23, v24, 16, 1
	v_add3_u32 v23, v24, v23, s60
	v_bfe_u32 v24, v25, 16, 1
	v_lshrrev_b32_e32 v23, 16, v23
	v_add3_u32 v24, v25, v24, s60
	v_and_or_b32 v23, v24, s61, v23
	v_bfe_u32 v24, v28, 16, 1
	v_add3_u32 v24, v28, v24, s60
	v_bfe_u32 v25, v29, 16, 1
	v_lshrrev_b32_e32 v24, 16, v24
	v_add3_u32 v25, v29, v25, s60
	v_and_or_b32 v24, v25, s61, v24
	v_bfe_u32 v25, v30, 16, 1
	v_add3_u32 v25, v30, v25, s60
	v_bfe_u32 v28, v31, 16, 1
	v_lshrrev_b32_e32 v25, 16, v25
	v_add3_u32 v28, v31, v28, s60
	v_and_or_b32 v25, v28, s61, v25
	v_or_b32_e32 v28, s0, v40
	v_lshlrev_b32_e32 v128, 11, v28
	v_lshl_add_u64 v[28:29], v[26:27], 0, v[128:129]
	flat_store_dwordx4 v[28:29], v[22:25]
	ds_read_b32 v22, v39 offset:64
	ds_read_b32 v23, v39 offset:196
	ds_read_b32 v24, v39 offset:328
	ds_read_b32 v25, v39 offset:460
	ds_read_b32 v28, v39 offset:592
	ds_read_b32 v29, v39 offset:724
	ds_read_b32 v30, v39 offset:856
	ds_read_b32 v31, v39 offset:988
	s_waitcnt lgkmcnt(0)
	v_bfe_u32 v32, v22, 16, 1
	v_add3_u32 v22, v22, v32, s60
	v_bfe_u32 v32, v23, 16, 1
	v_lshrrev_b32_e32 v22, 16, v22
	v_add3_u32 v23, v23, v32, s60
	v_and_or_b32 v22, v23, s61, v22
	v_bfe_u32 v23, v24, 16, 1
	v_add3_u32 v23, v24, v23, s60
	v_bfe_u32 v24, v25, 16, 1
	v_lshrrev_b32_e32 v23, 16, v23
	v_add3_u32 v24, v25, v24, s60
	v_and_or_b32 v23, v24, s61, v23
	v_bfe_u32 v24, v28, 16, 1
	v_add3_u32 v24, v28, v24, s60
	v_bfe_u32 v25, v29, 16, 1
	v_lshrrev_b32_e32 v24, 16, v24
	v_add3_u32 v25, v29, v25, s60
	v_and_or_b32 v24, v25, s61, v24
	v_bfe_u32 v25, v30, 16, 1
	v_add3_u32 v25, v30, v25, s60
	v_bfe_u32 v28, v31, 16, 1
	v_lshrrev_b32_e32 v25, 16, v25
	v_add3_u32 v28, v31, v28, s60
	v_and_or_b32 v25, v28, s61, v25
	v_or_b32_e32 v28, s0, v41
	v_lshlrev_b32_e32 v128, 11, v28
	v_lshl_add_u64 v[28:29], v[26:27], 0, v[128:129]
	flat_store_dwordx4 v[28:29], v[22:25]
	ds_read_b32 v22, v39 offset:96
	ds_read_b32 v23, v39 offset:228
	ds_read_b32 v24, v39 offset:360
	ds_read_b32 v25, v39 offset:492
	ds_read_b32 v28, v39 offset:624
	ds_read_b32 v29, v39 offset:756
	ds_read_b32 v30, v39 offset:888
	ds_read_b32 v31, v39 offset:1020
	s_waitcnt lgkmcnt(0)
	v_bfe_u32 v32, v22, 16, 1
	v_add3_u32 v22, v22, v32, s60
	v_bfe_u32 v32, v23, 16, 1
	v_lshrrev_b32_e32 v22, 16, v22
	v_add3_u32 v23, v23, v32, s60
	v_and_or_b32 v22, v23, s61, v22
	v_bfe_u32 v23, v24, 16, 1
	v_add3_u32 v23, v24, v23, s60
	v_bfe_u32 v24, v25, 16, 1
	v_lshrrev_b32_e32 v23, 16, v23
	v_add3_u32 v24, v25, v24, s60
	v_and_or_b32 v23, v24, s61, v23
	v_bfe_u32 v24, v28, 16, 1
	v_add3_u32 v24, v28, v24, s60
	v_bfe_u32 v25, v29, 16, 1
	v_lshrrev_b32_e32 v24, 16, v24
	v_add3_u32 v25, v29, v25, s60
	v_and_or_b32 v24, v25, s61, v24
	v_bfe_u32 v25, v30, 16, 1
	v_add3_u32 v25, v30, v25, s60
	v_bfe_u32 v28, v31, 16, 1
	v_lshrrev_b32_e32 v25, 16, v25
	v_add3_u32 v28, v31, v28, s60
	v_and_or_b32 v25, v28, s61, v25
	v_or_b32_e32 v28, s0, v42
	v_lshlrev_b32_e32 v128, 11, v28
	v_lshl_add_u64 v[26:27], v[26:27], 0, v[128:129]
	flat_store_dwordx4 v[26:27], v[22:25]
	s_waitcnt lgkmcnt(0)

; #define LAS __attribute__((address_space(3)))
; DEVQ unsigned pk2(float lo, float hi) { return f2bf(lo) | (f2bf(hi) << 16); }
; DEVQ void transpose_item(const float* W, int K, int N, bf16* WT, LAS float* scr, int item, int lane) {
;     const int nblk = N / 32, kb = item / nblk, nb = item % nblk, k0 = 64 * kb, n0 = 32 * nb;
; #pragma unroll 8
;     for (int i = 0; i < 32; ++i) { const int kk = 2 * i + (lane >> 5); scr[kk * 33 + (lane & 31)] = W[(size_t)(k0 + kk) * N + n0 + (lane & 31)]; }
;     asm volatile("s_waitcnt lgkmcnt(0)" ::: "memory");
;     const int c = lane & 7;
; #pragma unroll
;     for (int j = 0; j < 4; ++j) { const int n = (lane >> 3) + 8 * j; const LAS float* s = scr + (8 * c) * 33 + n;
;         v4u o; o.x = pk2(s[0 * 33], s[1 * 33]); o.y = pk2(s[2 * 33], s[3 * 33]); o.z = pk2(s[4 * 33], s[5 * 33]); o.w = pk2(s[6 * 33], s[7 * 33]);
;         *(v4u*)(WT + (size_t)(n0 + n) * K + k0 + 8 * c) = o; }
;     asm volatile("s_waitcnt lgkmcnt(0)" ::: "memory");
; }
.LBB0_762:
	v_add_u32_e32 v28, s1, v24
	v_mad_i64_i32 v[26:27], s[14:15], v28, s53, v[22:23]
	flat_load_dword v64, v[26:27]
	v_add_u32_e32 v26, 2, v28
	v_mad_i64_i32 v[26:27], s[14:15], v26, s53, v[22:23]
	s_add_i32 s1, s1, 16
	s_cmp_lg_u32 s1, 64
	flat_load_dword v65, v[26:27]
	v_add_u32_e32 v26, 4, v28
	v_mad_i64_i32 v[26:27], s[14:15], v26, s53, v[22:23]
	flat_load_dword v66, v[26:27]
	v_add_u32_e32 v26, 6, v28
	v_mad_i64_i32 v[26:27], s[14:15], v26, s53, v[22:23]
	flat_load_dword v67, v[26:27]
	v_add_u32_e32 v26, 8, v28
	v_mad_i64_i32 v[26:27], s[14:15], v26, s53, v[22:23]
	flat_load_dword v68, v[26:27]
	v_add_u32_e32 v26, 10, v28
	v_mad_i64_i32 v[26:27], s[14:15], v26, s53, v[22:23]
	flat_load_dword v69, v[26:27]
	v_add_u32_e32 v26, 12, v28
	v_mad_i64_i32 v[26:27], s[14:15], v26, s53, v[22:23]
	flat_load_dword v70, v[26:27]
	v_add_u32_e32 v26, 14, v28
	v_mad_i64_i32 v[26:27], s[14:15], v26, s53, v[22:23]
	flat_load_dword v71, v[26:27]
	s_waitcnt vmcnt(0) lgkmcnt(0)
	ds_write_b32 v25, v64
	ds_write_b32 v25, v65 offset:264
	ds_write_b32 v25, v66 offset:528
	ds_write_b32 v25, v67 offset:792
	ds_write_b32 v25, v68 offset:1056
	ds_write_b32 v25, v69 offset:1320
	ds_write_b32 v25, v70 offset:1584
	ds_write_b32 v25, v71 offset:1848
	v_add_u32_e32 v25, 0x840, v25
	s_cbranch_scc1 .LBB0_762
	s_waitcnt lgkmcnt(0)
	ds_read_b32 v22, v39
	ds_read_b32 v23, v39 offset:132
	ds_read_b32 v24, v39 offset:264
	ds_read_b32 v25, v39 offset:396
	ds_read_b32 v28, v39 offset:528
	ds_read_b32 v29, v39 offset:660
	ds_read_b32 v30, v39 offset:792
	ds_read_b32 v31, v39 offset:924
	s_waitcnt lgkmcnt(7)
	v_bfe_u32 v32, v22, 16, 1
	v_add3_u32 v22, v22, v32, s60
	s_waitcnt lgkmcnt(6)
	v_bfe_u32 v32, v23, 16, 1
	v_lshrrev_b32_e32 v22, 16, v22
	v_add3_u32 v23, v23, v32, s60
	v_and_or_b32 v22, v23, s61, v22
	s_waitcnt lgkmcnt(5)
	v_bfe_u32 v23, v24, 16, 1
	v_add3_u32 v23, v24, v23, s60
	s_waitcnt lgkmcnt(4)
	v_bfe_u32 v24, v25, 16, 1
	v_lshrrev_b32_e32 v23, 16, v23
	v_add3_u32 v24, v25, v24, s60
	v_and_or_b32 v23, v24, s61, v23
	s_waitcnt lgkmcnt(3)
	v_bfe_u32 v24, v28, 16, 1
	v_add3_u32 v24, v28, v24, s60
	s_waitcnt lgkmcnt(2)
	v_bfe_u32 v25, v29, 16, 1
	v_lshrrev_b32_e32 v24, 16, v24
	v_add3_u32 v25, v29, v25, s60
	v_and_or_b32 v24, v25, s61, v24
	s_waitcnt lgkmcnt(1)
	v_bfe_u32 v25, v30, 16, 1
	v_add3_u32 v25, v30, v25, s60
	s_waitcnt lgkmcnt(0)
	v_bfe_u32 v28, v31, 16, 1
	v_lshrrev_b32_e32 v25, 16, v25
	v_add3_u32 v28, v31, v28, s60
	v_and_or_b32 v25, v28, s61, v25
	v_or_b32_e32 v28, s0, v38
	s_ashr_i32 s3, s2, 31
	v_ashrrev_i32_e32 v29, 31, v28
	v_lshl_add_u64 v[26:27], s[2:3], 1, v[8:9]
	v_lshlrev_b64 v[28:29], 11, v[28:29]
	v_lshl_add_u64 v[28:29], v[26:27], 0, v[28:29]
	flat_store_dwordx4 v[28:29], v[22:25]
	ds_read_b32 v22, v39 offset:32
	ds_read_b32 v23, v39 offset:164
	ds_read_b32 v24, v39 offset:296
	ds_read_b32 v25, v39 offset:428
	ds_read_b32 v28, v39 offset:560
	ds_read_b32 v29, v39 offset:692
	ds_read_b32 v30, v39 offset:824
	ds_read_b32 v31, v39 offset:956
	s_waitcnt lgkmcnt(0)
	v_bfe_u32 v32, v22, 16, 1
	v_add3_u32 v22, v22, v32, s60
	v_bfe_u32 v32, v23, 16, 1
	v_lshrrev_b32_e32 v22, 16, v22
	v_add3_u32 v23, v23, v32, s60
	v_and_or_b32 v22, v23, s61, v22
	v_bfe_u32 v23, v24, 16, 1
	v_add3_u32 v23, v24, v23, s60
	v_bfe_u32 v24, v25, 16, 1
	v_lshrrev_b32_e32 v23, 16, v23
	v_add3_u32 v24, v25, v24, s60
	v_and_or_b32 v23, v24, s61, v23
	v_bfe_u32 v24, v28, 16, 1
	v_add3_u32 v24, v28, v24, s60
	v_bfe_u32 v25, v29, 16, 1
	v_lshrrev_b32_e32 v24, 16, v24
	v_add3_u32 v25, v29, v25, s60
	v_and_or_b32 v24, v25, s61, v24
	v_bfe_u32 v25, v30, 16, 1
	v_add3_u32 v25, v30, v25, s60
	v_bfe_u32 v28, v31, 16, 1
	v_lshrrev_b32_e32 v25, 16, v25
	v_add3_u32 v28, v31, v28, s60
	v_and_or_b32 v25, v28, s61, v25
	v_or_b32_e32 v28, s0, v40
	v_ashrrev_i32_e32 v29, 31, v28
	v_lshlrev_b64 v[28:29], 11, v[28:29]
	v_lshl_add_u64 v[28:29], v[26:27], 0, v[28:29]
	flat_store_dwordx4 v[28:29], v[22:25]
	ds_read_b32 v22, v39 offset:64
	ds_read_b32 v23, v39 offset:196
	ds_read_b32 v24, v39 offset:328
	ds_read_b32 v25, v39 offset:460
	ds_read_b32 v28, v39 offset:592
	ds_read_b32 v29, v39 offset:724
	ds_read_b32 v30, v39 offset:856
	ds_read_b32 v31, v39 offset:988
	s_waitcnt lgkmcnt(0)
	v_bfe_u32 v32, v22, 16, 1
	v_add3_u32 v22, v22, v32, s60
	v_bfe_u32 v32, v23, 16, 1
	v_lshrrev_b32_e32 v22, 16, v22
	v_add3_u32 v23, v23, v32, s60
	v_and_or_b32 v22, v23, s61, v22
	v_bfe_u32 v23, v24, 16, 1
	v_add3_u32 v23, v24, v23, s60
	v_bfe_u32 v24, v25, 16, 1
	v_lshrrev_b32_e32 v23, 16, v23
	v_add3_u32 v24, v25, v24, s60
	v_and_or_b32 v23, v24, s61, v23
	v_bfe_u32 v24, v28, 16, 1
	v_add3_u32 v24, v28, v24, s60
	v_bfe_u32 v25, v29, 16, 1
	v_lshrrev_b32_e32 v24, 16, v24
	v_add3_u32 v25, v29, v25, s60
	v_and_or_b32 v24, v25, s61, v24
	v_bfe_u32 v25, v30, 16, 1
	v_add3_u32 v25, v30, v25, s60
	v_bfe_u32 v28, v31, 16, 1
	v_lshrrev_b32_e32 v25, 16, v25
	v_add3_u32 v28, v31, v28, s60
	v_and_or_b32 v25, v28, s61, v25
	v_or_b32_e32 v28, s0, v41
	v_ashrrev_i32_e32 v29, 31, v28
	v_lshlrev_b64 v[28:29], 11, v[28:29]
	v_lshl_add_u64 v[28:29], v[26:27], 0, v[28:29]
	flat_store_dwordx4 v[28:29], v[22:25]
	ds_read_b32 v22, v39 offset:96
	ds_read_b32 v23, v39 offset:228
	ds_read_b32 v24, v39 offset:360
	ds_read_b32 v25, v39 offset:492
	ds_read_b32 v28, v39 offset:624
	ds_read_b32 v29, v39 offset:756
	ds_read_b32 v30, v39 offset:888
	ds_read_b32 v31, v39 offset:1020
	s_waitcnt lgkmcnt(0)
	v_bfe_u32 v32, v22, 16, 1
	v_add3_u32 v22, v22, v32, s60
	v_bfe_u32 v32, v23, 16, 1
	v_lshrrev_b32_e32 v22, 16, v22
	v_add3_u32 v23, v23, v32, s60
	v_and_or_b32 v22, v23, s61, v22
	v_bfe_u32 v23, v24, 16, 1
	v_add3_u32 v23, v24, v23, s60
	v_bfe_u32 v24, v25, 16, 1
	v_lshrrev_b32_e32 v23, 16, v23
	v_add3_u32 v24, v25, v24, s60
	v_and_or_b32 v23, v24, s61, v23
	v_bfe_u32 v24, v28, 16, 1
	v_add3_u32 v24, v28, v24, s60
	v_bfe_u32 v25, v29, 16, 1
	v_lshrrev_b32_e32 v24, 16, v24
	v_add3_u32 v25, v29, v25, s60
	v_and_or_b32 v24, v25, s61, v24
	v_bfe_u32 v25, v30, 16, 1
	v_add3_u32 v25, v30, v25, s60
	v_bfe_u32 v28, v31, 16, 1
	v_lshrrev_b32_e32 v25, 16, v25
	v_add3_u32 v28, v31, v28, s60
	v_and_or_b32 v25, v28, s61, v25
	v_or_b32_e32 v28, s0, v42
	v_ashrrev_i32_e32 v29, 31, v28
	v_lshlrev_b64 v[28:29], 11, v[28:29]
	v_lshl_add_u64 v[26:27], v[26:27], 0, v[28:29]
	flat_store_dwordx4 v[26:27], v[22:25]
	s_waitcnt lgkmcnt(0)
	s_branch .LBB0_731
